# cache-policy hint: nt on the FFN-hidden (H) stores of the P9 SwiGLU epilogue
# speedup vs baseline: 1.0037x; 1.0013x over previous
.LBB0_1206:
	s_add_u32 s28, s22, 0xfffc0080
	s_addc_u32 s29, s23, -1
	s_add_i32 s84, 0, 0x10000
	v_add_u32_e32 v140, s84, v143
	ds_read_b128 v[146:149], v140
	ds_read_b128 v[150:153], v140 offset:1024
	ds_read_b128 v[154:157], v140 offset:2048
	ds_read_b128 v[158:161], v140 offset:3072
	s_cmp_eq_u32 s83, 12
	s_cselect_b32 s35, s13, s29
	s_cselect_b32 s34, s79, s28
	s_cselect_b32 s29, s11, s82
	s_cselect_b32 s28, s80, s81
	v_lshl_add_u64 v[140:141], s[22:23], 0, v[136:137]
	s_add_i32 m0, s19, 0xc000
	ds_read_b128 v[162:165], v145
	ds_read_b128 v[166:169], v145 offset:1024
	ds_read_b128 v[170:173], v145 offset:2048
	ds_read_b128 v[174:177], v145 offset:3072
	ds_read_b128 v[178:181], v145 offset:4096
	ds_read_b128 v[182:185], v145 offset:5120
	ds_read_b128 v[186:189], v145 offset:6144
	ds_read_b128 v[190:193], v145 offset:7168
	global_load_lds_dwordx4 v[140:141], off
	v_lshl_add_u64 v[140:141], s[22:23], 0, v[138:139]
	s_add_i32 m0, s19, 0xe000
	s_nop 0
	global_load_lds_dwordx4 v[140:141], off
	s_waitcnt lgkmcnt(8)
	s_barrier
	s_waitcnt lgkmcnt(0)
	s_setprio 1
	s_waitcnt lgkmcnt(0)
	v_mfma_f32_16x16x32_bf16 v[126:129], v[146:149], v[162:165], v[126:129]
	v_mfma_f32_16x16x32_bf16 v[118:121], v[154:157], v[162:165], v[118:121]
	v_mfma_f32_16x16x32_bf16 v[110:113], v[146:149], v[170:173], v[110:113]
	v_mfma_f32_16x16x32_bf16 v[102:105], v[154:157], v[170:173], v[102:105]
	v_mfma_f32_16x16x32_bf16 v[94:97], v[146:149], v[178:181], v[94:97]
	v_mfma_f32_16x16x32_bf16 v[86:89], v[154:157], v[178:181], v[86:89]
	v_mfma_f32_16x16x32_bf16 v[78:81], v[146:149], v[186:189], v[78:81]
	v_mfma_f32_16x16x32_bf16 v[70:73], v[154:157], v[186:189], v[70:73]
	v_mfma_f32_16x16x32_bf16 v[126:129], v[150:153], v[166:169], v[126:129]
	v_mfma_f32_16x16x32_bf16 v[118:121], v[158:161], v[166:169], v[118:121]
	v_mfma_f32_16x16x32_bf16 v[110:113], v[150:153], v[174:177], v[110:113]
	v_mfma_f32_16x16x32_bf16 v[102:105], v[158:161], v[174:177], v[102:105]
	v_mfma_f32_16x16x32_bf16 v[94:97], v[150:153], v[182:185], v[94:97]
	v_mfma_f32_16x16x32_bf16 v[86:89], v[158:161], v[182:185], v[86:89]
	v_mfma_f32_16x16x32_bf16 v[78:81], v[150:153], v[190:193], v[78:81]
	v_mfma_f32_16x16x32_bf16 v[70:73], v[158:161], v[190:193], v[70:73]
	s_setprio 0
	s_barrier
	s_add_i32 s86, 0, 0x14000
	v_add_u32_e32 v140, s86, v143
	s_add_i32 s84, s84, s63
	ds_read_b128 v[194:197], v140
	ds_read_b128 v[198:201], v140 offset:1024
	ds_read_b128 v[202:205], v140 offset:2048
	ds_read_b128 v[206:209], v140 offset:3072
	v_lshl_add_u64 v[140:141], s[28:29], 0, v[0:1]
	s_mov_b32 m0, s84
	v_lshl_add_u64 v[212:213], s[28:29], 0, v[134:135]
	global_load_lds_dwordx4 v[140:141], off
	s_add_i32 m0, s84, 0x2000
	s_nop 0
	global_load_lds_dwordx4 v[212:213], off
	s_barrier
	s_waitcnt lgkmcnt(0)
	s_setprio 1
	s_waitcnt lgkmcnt(0)
	v_mfma_f32_16x16x32_bf16 v[122:125], v[194:197], v[162:165], v[122:125]
	v_mfma_f32_16x16x32_bf16 v[114:117], v[202:205], v[162:165], v[114:117]
	v_mfma_f32_16x16x32_bf16 v[106:109], v[194:197], v[170:173], v[106:109]
	v_mfma_f32_16x16x32_bf16 v[98:101], v[202:205], v[170:173], v[98:101]
	v_mfma_f32_16x16x32_bf16 v[90:93], v[194:197], v[178:181], v[90:93]
	v_mfma_f32_16x16x32_bf16 v[82:85], v[202:205], v[178:181], v[82:85]
	v_mfma_f32_16x16x32_bf16 v[74:77], v[194:197], v[186:189], v[74:77]
	v_mfma_f32_16x16x32_bf16 v[66:69], v[202:205], v[186:189], v[66:69]
	v_mfma_f32_16x16x32_bf16 v[122:125], v[198:201], v[166:169], v[122:125]
	v_mfma_f32_16x16x32_bf16 v[114:117], v[206:209], v[166:169], v[114:117]
	v_mfma_f32_16x16x32_bf16 v[106:109], v[198:201], v[174:177], v[106:109]
	v_mfma_f32_16x16x32_bf16 v[98:101], v[206:209], v[174:177], v[98:101]
	v_mfma_f32_16x16x32_bf16 v[90:93], v[198:201], v[182:185], v[90:93]
	v_mfma_f32_16x16x32_bf16 v[82:85], v[206:209], v[182:185], v[82:85]
	v_mfma_f32_16x16x32_bf16 v[74:77], v[198:201], v[190:193], v[74:77]
	v_mfma_f32_16x16x32_bf16 v[66:69], v[206:209], v[190:193], v[66:69]
	s_setprio 0
	s_mov_b32 m0, s19
	v_lshl_add_u64 v[214:215], s[34:35], 0, v[130:131]
	s_barrier
	ds_read_b128 v[162:165], v145 offset:16384
	ds_read_b128 v[166:169], v145 offset:17408
	ds_read_b128 v[170:173], v145 offset:18432
	ds_read_b128 v[174:177], v145 offset:19456
	ds_read_b128 v[178:181], v145 offset:20480
	ds_read_b128 v[182:185], v145 offset:21504
	ds_read_b128 v[186:189], v145 offset:22528
	ds_read_b128 v[190:193], v145 offset:23552
	global_load_lds_dwordx4 v[214:215], off
	v_lshl_add_u64 v[216:217], s[34:35], 0, v[132:133]
	s_mov_b32 m0, s21
	s_nop 0
	global_load_lds_dwordx4 v[216:217], off
	s_barrier
	s_waitcnt lgkmcnt(0)
	s_setprio 1
	s_waitcnt lgkmcnt(0)
	v_mfma_f32_16x16x32_bf16 v[62:65], v[146:149], v[162:165], v[62:65]
	v_mfma_f32_16x16x32_bf16 v[54:57], v[154:157], v[162:165], v[54:57]
	v_mfma_f32_16x16x32_bf16 v[46:49], v[146:149], v[170:173], v[46:49]
	v_mfma_f32_16x16x32_bf16 v[38:41], v[154:157], v[170:173], v[38:41]
	v_mfma_f32_16x16x32_bf16 v[30:33], v[146:149], v[178:181], v[30:33]
	v_mfma_f32_16x16x32_bf16 v[22:25], v[154:157], v[178:181], v[22:25]
	v_mfma_f32_16x16x32_bf16 v[14:17], v[146:149], v[186:189], v[14:17]
	v_mfma_f32_16x16x32_bf16 v[6:9], v[154:157], v[186:189], v[6:9]
	v_mfma_f32_16x16x32_bf16 v[62:65], v[150:153], v[166:169], v[62:65]
	v_mfma_f32_16x16x32_bf16 v[54:57], v[158:161], v[166:169], v[54:57]
	v_mfma_f32_16x16x32_bf16 v[46:49], v[150:153], v[174:177], v[46:49]
	v_mfma_f32_16x16x32_bf16 v[38:41], v[158:161], v[174:177], v[38:41]
	v_mfma_f32_16x16x32_bf16 v[30:33], v[150:153], v[182:185], v[30:33]
	v_mfma_f32_16x16x32_bf16 v[22:25], v[158:161], v[182:185], v[22:25]
	v_mfma_f32_16x16x32_bf16 v[14:17], v[150:153], v[190:193], v[14:17]
	v_mfma_f32_16x16x32_bf16 v[6:9], v[158:161], v[190:193], v[6:9]
	s_setprio 0
	s_barrier
	s_add_u32 s84, s28, 0x40000
	s_addc_u32 s85, s29, 0
	s_add_i32 s86, s86, s63
	v_lshl_add_u64 v[146:147], s[84:85], 0, v[0:1]
	s_mov_b32 m0, s86
	s_nop 0
	global_load_lds_dwordx4 v[146:147], off
	v_lshl_add_u64 v[146:147], s[84:85], 0, v[134:135]
	s_add_i32 m0, s86, 0x2000
	s_nop 0
	global_load_lds_dwordx4 v[146:147], off
	s_waitcnt vmcnt(6)
	s_barrier
	s_setprio 1
	v_mfma_f32_16x16x32_bf16 v[58:61], v[194:197], v[162:165], v[58:61]
	v_mfma_f32_16x16x32_bf16 v[50:53], v[202:205], v[162:165], v[50:53]
	v_mfma_f32_16x16x32_bf16 v[42:45], v[194:197], v[170:173], v[42:45]
	v_mfma_f32_16x16x32_bf16 v[34:37], v[202:205], v[170:173], v[34:37]
	v_mfma_f32_16x16x32_bf16 v[26:29], v[194:197], v[178:181], v[26:29]
	v_mfma_f32_16x16x32_bf16 v[18:21], v[202:205], v[178:181], v[18:21]
	v_mfma_f32_16x16x32_bf16 v[10:13], v[194:197], v[186:189], v[10:13]
	v_mfma_f32_16x16x32_bf16 v[2:5], v[202:205], v[186:189], v[2:5]
	v_mfma_f32_16x16x32_bf16 v[58:61], v[198:201], v[166:169], v[58:61]
	v_mfma_f32_16x16x32_bf16 v[50:53], v[206:209], v[166:169], v[50:53]
	v_mfma_f32_16x16x32_bf16 v[42:45], v[198:201], v[174:177], v[42:45]
	v_mfma_f32_16x16x32_bf16 v[34:37], v[206:209], v[174:177], v[34:37]
	v_mfma_f32_16x16x32_bf16 v[26:29], v[198:201], v[182:185], v[26:29]
	v_mfma_f32_16x16x32_bf16 v[18:21], v[206:209], v[182:185], v[18:21]
	v_mfma_f32_16x16x32_bf16 v[10:13], v[198:201], v[190:193], v[10:13]
	v_mfma_f32_16x16x32_bf16 v[2:5], v[206:209], v[190:193], v[2:5]
	s_setprio 0
	s_add_i32 s84, 0, 0x18000
	v_add_u32_e32 v158, s84, v143
	s_barrier
	ds_read_b128 v[146:149], v158
	ds_read_b128 v[150:153], v158 offset:1024
	ds_read_b128 v[154:157], v158 offset:2048
	ds_read_b128 v[158:161], v158 offset:3072
	s_add_u32 s34, s34, 0x40000
	s_addc_u32 s35, s35, 0
	s_mov_b32 m0, s64
	v_lshl_add_u64 v[194:195], s[34:35], 0, v[130:131]
	ds_read_b128 v[162:165], v145 offset:32768
	ds_read_b128 v[166:169], v145 offset:33792
	ds_read_b128 v[170:173], v145 offset:34816
	ds_read_b128 v[174:177], v145 offset:35840
	ds_read_b128 v[178:181], v145 offset:36864
	ds_read_b128 v[182:185], v145 offset:37888
	ds_read_b128 v[186:189], v145 offset:38912
	ds_read_b128 v[190:193], v145 offset:39936
	global_load_lds_dwordx4 v[194:195], off
	v_lshl_add_u64 v[194:195], s[34:35], 0, v[132:133]
	s_mov_b32 m0, s65
	s_nop 0
	global_load_lds_dwordx4 v[194:195], off
	s_waitcnt lgkmcnt(8)
	s_barrier
	s_waitcnt lgkmcnt(0)
	s_setprio 1
	s_waitcnt lgkmcnt(0)
	v_mfma_f32_16x16x32_bf16 v[126:129], v[146:149], v[162:165], v[126:129]
	v_mfma_f32_16x16x32_bf16 v[118:121], v[154:157], v[162:165], v[118:121]
	v_mfma_f32_16x16x32_bf16 v[110:113], v[146:149], v[170:173], v[110:113]
	v_mfma_f32_16x16x32_bf16 v[102:105], v[154:157], v[170:173], v[102:105]
	v_mfma_f32_16x16x32_bf16 v[94:97], v[146:149], v[178:181], v[94:97]
	v_mfma_f32_16x16x32_bf16 v[86:89], v[154:157], v[178:181], v[86:89]
	v_mfma_f32_16x16x32_bf16 v[78:81], v[146:149], v[186:189], v[78:81]
	v_mfma_f32_16x16x32_bf16 v[70:73], v[154:157], v[186:189], v[70:73]
	v_mfma_f32_16x16x32_bf16 v[126:129], v[150:153], v[166:169], v[126:129]
	v_mfma_f32_16x16x32_bf16 v[118:121], v[158:161], v[166:169], v[118:121]
	v_mfma_f32_16x16x32_bf16 v[110:113], v[150:153], v[174:177], v[110:113]
	v_mfma_f32_16x16x32_bf16 v[102:105], v[158:161], v[174:177], v[102:105]
	v_mfma_f32_16x16x32_bf16 v[94:97], v[150:153], v[182:185], v[94:97]
	v_mfma_f32_16x16x32_bf16 v[86:89], v[158:161], v[182:185], v[86:89]
	v_mfma_f32_16x16x32_bf16 v[78:81], v[150:153], v[190:193], v[78:81]
	v_mfma_f32_16x16x32_bf16 v[70:73], v[158:161], v[190:193], v[70:73]
	s_setprio 0
	s_barrier
	s_add_i32 s34, 0, 0x1c000
	s_add_i32 s35, s84, s63
	v_add_u32_e32 v206, s34, v143
	v_lshl_add_u64 v[140:141], v[140:141], 0, s[56:57]
	s_mov_b32 m0, s35
	ds_read_b128 v[194:197], v206
	ds_read_b128 v[198:201], v206 offset:1024
	ds_read_b128 v[202:205], v206 offset:2048
	ds_read_b128 v[206:209], v206 offset:3072
	global_load_lds_dwordx4 v[140:141], off
	v_lshl_add_u64 v[140:141], v[212:213], 0, s[56:57]
	s_add_i32 m0, s35, 0x2000
	s_nop 0
	global_load_lds_dwordx4 v[140:141], off
	s_barrier
	s_waitcnt lgkmcnt(0)
	s_setprio 1
	s_waitcnt lgkmcnt(0)
	v_mfma_f32_16x16x32_bf16 v[122:125], v[194:197], v[162:165], v[122:125]
	v_mfma_f32_16x16x32_bf16 v[114:117], v[202:205], v[162:165], v[114:117]
	v_mfma_f32_16x16x32_bf16 v[106:109], v[194:197], v[170:173], v[106:109]
	v_mfma_f32_16x16x32_bf16 v[98:101], v[202:205], v[170:173], v[98:101]
	v_mfma_f32_16x16x32_bf16 v[90:93], v[194:197], v[178:181], v[90:93]
	v_mfma_f32_16x16x32_bf16 v[82:85], v[202:205], v[178:181], v[82:85]
	v_mfma_f32_16x16x32_bf16 v[74:77], v[194:197], v[186:189], v[74:77]
	v_mfma_f32_16x16x32_bf16 v[66:69], v[202:205], v[186:189], v[66:69]
	v_mfma_f32_16x16x32_bf16 v[122:125], v[198:201], v[166:169], v[122:125]
	v_mfma_f32_16x16x32_bf16 v[114:117], v[206:209], v[166:169], v[114:117]
	v_mfma_f32_16x16x32_bf16 v[106:109], v[198:201], v[174:177], v[106:109]
	v_mfma_f32_16x16x32_bf16 v[98:101], v[206:209], v[174:177], v[98:101]
	v_mfma_f32_16x16x32_bf16 v[90:93], v[198:201], v[182:185], v[90:93]
	v_mfma_f32_16x16x32_bf16 v[82:85], v[206:209], v[182:185], v[82:85]
	v_mfma_f32_16x16x32_bf16 v[74:77], v[198:201], v[190:193], v[74:77]
	v_mfma_f32_16x16x32_bf16 v[66:69], v[206:209], v[190:193], v[66:69]
	s_setprio 0
	s_mov_b32 m0, s76
	v_lshl_add_u64 v[140:141], v[214:215], 0, s[56:57]
	s_barrier
	ds_read_b128 v[162:165], v145 offset:49152
	ds_read_b128 v[166:169], v145 offset:50176
	ds_read_b128 v[170:173], v145 offset:51200
	ds_read_b128 v[174:177], v145 offset:52224
	ds_read_b128 v[178:181], v145 offset:53248
	ds_read_b128 v[182:185], v145 offset:54272
	ds_read_b128 v[186:189], v145 offset:55296
	ds_read_b128 v[190:193], v145 offset:56320
	global_load_lds_dwordx4 v[140:141], off
	v_lshl_add_u64 v[140:141], v[216:217], 0, s[56:57]
	s_mov_b32 m0, s77
	s_nop 0
	global_load_lds_dwordx4 v[140:141], off
	s_barrier
	s_waitcnt lgkmcnt(0)
	s_setprio 1
	s_waitcnt lgkmcnt(0)
	v_mfma_f32_16x16x32_bf16 v[62:65], v[146:149], v[162:165], v[62:65]
	v_mfma_f32_16x16x32_bf16 v[54:57], v[154:157], v[162:165], v[54:57]
	v_mfma_f32_16x16x32_bf16 v[46:49], v[146:149], v[170:173], v[46:49]
	v_mfma_f32_16x16x32_bf16 v[38:41], v[154:157], v[170:173], v[38:41]
	v_mfma_f32_16x16x32_bf16 v[30:33], v[146:149], v[178:181], v[30:33]
	v_mfma_f32_16x16x32_bf16 v[22:25], v[154:157], v[178:181], v[22:25]
	v_mfma_f32_16x16x32_bf16 v[14:17], v[146:149], v[186:189], v[14:17]
	v_mfma_f32_16x16x32_bf16 v[6:9], v[154:157], v[186:189], v[6:9]
	v_mfma_f32_16x16x32_bf16 v[62:65], v[150:153], v[166:169], v[62:65]
	v_mfma_f32_16x16x32_bf16 v[54:57], v[158:161], v[166:169], v[54:57]
	v_mfma_f32_16x16x32_bf16 v[46:49], v[150:153], v[174:177], v[46:49]
	v_mfma_f32_16x16x32_bf16 v[38:41], v[158:161], v[174:177], v[38:41]
	v_mfma_f32_16x16x32_bf16 v[30:33], v[150:153], v[182:185], v[30:33]
	v_mfma_f32_16x16x32_bf16 v[22:25], v[158:161], v[182:185], v[22:25]
	v_mfma_f32_16x16x32_bf16 v[14:17], v[150:153], v[190:193], v[14:17]
	v_mfma_f32_16x16x32_bf16 v[6:9], v[158:161], v[190:193], v[6:9]
	s_setprio 0
	s_barrier
	s_add_u32 s28, s28, 0x40080
	s_addc_u32 s29, s29, 0
	s_add_i32 s34, s34, s63
	v_lshl_add_u64 v[140:141], s[28:29], 0, v[0:1]
	s_mov_b32 m0, s34
	s_nop 0
	global_load_lds_dwordx4 v[140:141], off
	v_lshl_add_u64 v[140:141], s[28:29], 0, v[134:135]
	s_add_i32 m0, s34, 0x2000
	s_nop 0
	global_load_lds_dwordx4 v[140:141], off
	s_waitcnt vmcnt(6)
	s_barrier
	s_setprio 1
	v_mfma_f32_16x16x32_bf16 v[58:61], v[194:197], v[162:165], v[58:61]
	v_mfma_f32_16x16x32_bf16 v[50:53], v[202:205], v[162:165], v[50:53]
	v_mfma_f32_16x16x32_bf16 v[42:45], v[194:197], v[170:173], v[42:45]
	v_mfma_f32_16x16x32_bf16 v[34:37], v[202:205], v[170:173], v[34:37]
	v_mfma_f32_16x16x32_bf16 v[26:29], v[194:197], v[178:181], v[26:29]
	v_mfma_f32_16x16x32_bf16 v[18:21], v[202:205], v[178:181], v[18:21]
	v_mfma_f32_16x16x32_bf16 v[10:13], v[194:197], v[186:189], v[10:13]
	v_mfma_f32_16x16x32_bf16 v[2:5], v[202:205], v[186:189], v[2:5]
	v_mfma_f32_16x16x32_bf16 v[58:61], v[198:201], v[166:169], v[58:61]
	v_mfma_f32_16x16x32_bf16 v[50:53], v[206:209], v[166:169], v[50:53]
	v_mfma_f32_16x16x32_bf16 v[42:45], v[198:201], v[174:177], v[42:45]
	v_mfma_f32_16x16x32_bf16 v[34:37], v[206:209], v[174:177], v[34:37]
	v_mfma_f32_16x16x32_bf16 v[26:29], v[198:201], v[182:185], v[26:29]
	v_mfma_f32_16x16x32_bf16 v[18:21], v[206:209], v[182:185], v[18:21]
	v_mfma_f32_16x16x32_bf16 v[10:13], v[198:201], v[190:193], v[10:13]
	v_mfma_f32_16x16x32_bf16 v[2:5], v[206:209], v[190:193], v[2:5]
	s_setprio 0
	s_add_i32 s83, s83, 2
	s_add_u32 s22, s22, 0x100
	s_addc_u32 s23, s23, 0
	s_add_u32 s81, s81, 0x100
	s_addc_u32 s82, s82, 0
	s_cmp_gt_u32 s83, 13
	s_barrier
	s_cbranch_scc0 .LBB0_1206
	v_readlane_b32 s80, v254, 55
	v_lshl_or_b32 v148, s18, 7, v144
	v_readlane_b32 s81, v254, 56
	v_lshl_add_u32 v146, s20, 8, v142
	v_ashrrev_i32_e32 v149, 31, v148
	s_movk_i32 s11, 0x1600
	s_and_b64 vcc, exec, s[0:1]
	s_mov_b32 s18, s10
	s_mov_b32 s20, s12
	s_mov_b64 s[34:35], s[16:17]
	v_lshlrev_b64 v[148:149], 1, v[148:149]
	v_mov_b64_e32 v[140:141], s[80:81]
	v_lshl_add_u64 v[150:151], v[140:141], 0, v[148:149]
	v_mul_f32_e32 v152, 0xbfb8aa3b, v126
	v_mul_f32_e32 v153, 0xbfb8aa3b, v127
	v_mul_f32_e32 v154, 0xbfb8aa3b, v128
	v_mul_f32_e32 v155, 0xbfb8aa3b, v129
	v_mul_f32_e32 v156, 0xbfb8aa3b, v118
	v_mul_f32_e32 v157, 0xbfb8aa3b, v119
	v_mul_f32_e32 v158, 0xbfb8aa3b, v120
	v_mul_f32_e32 v159, 0xbfb8aa3b, v121
	v_exp_f32_e32 v152, v152
	v_exp_f32_e32 v153, v153
	v_exp_f32_e32 v154, v154
	v_exp_f32_e32 v155, v155
	v_exp_f32_e32 v156, v156
	v_exp_f32_e32 v157, v157
	v_exp_f32_e32 v158, v158
	v_exp_f32_e32 v159, v159
	v_mov_b32_e32 v166, v146
	v_mad_i64_i32 v[164:165], s[22:23], v166, s11, v[150:151]
	v_add_f32_e32 v152, 1.0, v152
	v_add_f32_e32 v153, 1.0, v153
	v_add_f32_e32 v154, 1.0, v154
	v_add_f32_e32 v155, 1.0, v155
	v_add_f32_e32 v156, 1.0, v156
	v_add_f32_e32 v157, 1.0, v157
	v_add_f32_e32 v158, 1.0, v158
	v_add_f32_e32 v159, 1.0, v159
	v_rcp_f32_e32 v152, v152
	v_rcp_f32_e32 v153, v153
	v_rcp_f32_e32 v154, v154
	v_rcp_f32_e32 v155, v155
	v_rcp_f32_e32 v156, v156
	v_rcp_f32_e32 v157, v157
	v_rcp_f32_e32 v158, v158
	v_rcp_f32_e32 v159, v159
	s_nop 0
	v_mul_f32_e32 v126, v126, v152
	v_mul_f32_e32 v127, v127, v153
	v_mul_f32_e32 v128, v128, v154
	v_mul_f32_e32 v129, v129, v155
	v_mul_f32_e32 v118, v118, v156
	v_mul_f32_e32 v119, v119, v157
	v_mul_f32_e32 v120, v120, v158
	v_mul_f32_e32 v121, v121, v159
	v_mul_f32_e32 v126, v126, v122
	v_mul_f32_e32 v127, v127, v123
	v_mul_f32_e32 v128, v128, v124
	v_mul_f32_e32 v129, v129, v125
	v_mul_f32_e32 v118, v118, v114
	v_mul_f32_e32 v119, v119, v115
	v_mul_f32_e32 v120, v120, v116
	v_mul_f32_e32 v121, v121, v117
	v_cvt_pk_bf16_f32 v160, v126, v127
	v_cvt_pk_bf16_f32 v161, v128, v129
	v_cvt_pk_bf16_f32 v162, v118, v119
	v_cvt_pk_bf16_f32 v163, v120, v121
	global_store_dwordx4 v[164:165], v[160:163], off nt
	v_mul_f32_e32 v152, 0xbfb8aa3b, v110
	v_mul_f32_e32 v153, 0xbfb8aa3b, v111
	v_mul_f32_e32 v154, 0xbfb8aa3b, v112
	v_mul_f32_e32 v155, 0xbfb8aa3b, v113
	v_mul_f32_e32 v156, 0xbfb8aa3b, v102
	v_mul_f32_e32 v157, 0xbfb8aa3b, v103
	v_mul_f32_e32 v158, 0xbfb8aa3b, v104
	v_mul_f32_e32 v159, 0xbfb8aa3b, v105
	v_exp_f32_e32 v152, v152
	v_exp_f32_e32 v153, v153
	v_exp_f32_e32 v154, v154
	v_exp_f32_e32 v155, v155
	v_exp_f32_e32 v156, v156
	v_exp_f32_e32 v157, v157
	v_exp_f32_e32 v158, v158
	v_exp_f32_e32 v159, v159
	v_add_u32_e32 v166, 16, v146
	v_mad_i64_i32 v[164:165], s[22:23], v166, s11, v[150:151]
	v_add_f32_e32 v152, 1.0, v152
	v_add_f32_e32 v153, 1.0, v153
	v_add_f32_e32 v154, 1.0, v154
	v_add_f32_e32 v155, 1.0, v155
	v_add_f32_e32 v156, 1.0, v156
	v_add_f32_e32 v157, 1.0, v157
	v_add_f32_e32 v158, 1.0, v158
	v_add_f32_e32 v159, 1.0, v159
	v_rcp_f32_e32 v152, v152
	v_rcp_f32_e32 v153, v153
	v_rcp_f32_e32 v154, v154
	v_rcp_f32_e32 v155, v155
	v_rcp_f32_e32 v156, v156
	v_rcp_f32_e32 v157, v157
	v_rcp_f32_e32 v158, v158
	v_rcp_f32_e32 v159, v159
	s_nop 0
	v_mul_f32_e32 v110, v110, v152
	v_mul_f32_e32 v111, v111, v153
	v_mul_f32_e32 v112, v112, v154
	v_mul_f32_e32 v113, v113, v155
	v_mul_f32_e32 v102, v102, v156
	v_mul_f32_e32 v103, v103, v157
	v_mul_f32_e32 v104, v104, v158
	v_mul_f32_e32 v105, v105, v159
	v_mul_f32_e32 v110, v110, v106
	v_mul_f32_e32 v111, v111, v107
	v_mul_f32_e32 v112, v112, v108
	v_mul_f32_e32 v113, v113, v109
	v_mul_f32_e32 v102, v102, v98
	v_mul_f32_e32 v103, v103, v99
	v_mul_f32_e32 v104, v104, v100
	v_mul_f32_e32 v105, v105, v101
	v_cvt_pk_bf16_f32 v160, v110, v111
	v_cvt_pk_bf16_f32 v161, v112, v113
	v_cvt_pk_bf16_f32 v162, v102, v103
	v_cvt_pk_bf16_f32 v163, v104, v105
	global_store_dwordx4 v[164:165], v[160:163], off nt
	v_mul_f32_e32 v152, 0xbfb8aa3b, v94
	v_mul_f32_e32 v153, 0xbfb8aa3b, v95
	v_mul_f32_e32 v154, 0xbfb8aa3b, v96
	v_mul_f32_e32 v155, 0xbfb8aa3b, v97
	v_mul_f32_e32 v156, 0xbfb8aa3b, v86
	v_mul_f32_e32 v157, 0xbfb8aa3b, v87
	v_mul_f32_e32 v158, 0xbfb8aa3b, v88
	v_mul_f32_e32 v159, 0xbfb8aa3b, v89
	v_exp_f32_e32 v152, v152
	v_exp_f32_e32 v153, v153
	v_exp_f32_e32 v154, v154
	v_exp_f32_e32 v155, v155
	v_exp_f32_e32 v156, v156
	v_exp_f32_e32 v157, v157
	v_exp_f32_e32 v158, v158
	v_exp_f32_e32 v159, v159
	v_add_u32_e32 v166, 32, v146
	v_mad_i64_i32 v[164:165], s[22:23], v166, s11, v[150:151]
	v_add_f32_e32 v152, 1.0, v152
	v_add_f32_e32 v153, 1.0, v153
	v_add_f32_e32 v154, 1.0, v154
	v_add_f32_e32 v155, 1.0, v155
	v_add_f32_e32 v156, 1.0, v156
	v_add_f32_e32 v157, 1.0, v157
	v_add_f32_e32 v158, 1.0, v158
	v_add_f32_e32 v159, 1.0, v159
	v_rcp_f32_e32 v152, v152
	v_rcp_f32_e32 v153, v153
	v_rcp_f32_e32 v154, v154
	v_rcp_f32_e32 v155, v155
	v_rcp_f32_e32 v156, v156
	v_rcp_f32_e32 v157, v157
	v_rcp_f32_e32 v158, v158
	v_rcp_f32_e32 v159, v159
	s_nop 0
	v_mul_f32_e32 v94, v94, v152
	v_mul_f32_e32 v95, v95, v153
	v_mul_f32_e32 v96, v96, v154
	v_mul_f32_e32 v97, v97, v155
	v_mul_f32_e32 v86, v86, v156
	v_mul_f32_e32 v87, v87, v157
	v_mul_f32_e32 v88, v88, v158
	v_mul_f32_e32 v89, v89, v159
	v_mul_f32_e32 v94, v94, v90
	v_mul_f32_e32 v95, v95, v91
	v_mul_f32_e32 v96, v96, v92
	v_mul_f32_e32 v97, v97, v93
	v_mul_f32_e32 v86, v86, v82
	v_mul_f32_e32 v87, v87, v83
	v_mul_f32_e32 v88, v88, v84
	v_mul_f32_e32 v89, v89, v85
	v_cvt_pk_bf16_f32 v160, v94, v95
	v_cvt_pk_bf16_f32 v161, v96, v97
	v_cvt_pk_bf16_f32 v162, v86, v87
	v_cvt_pk_bf16_f32 v163, v88, v89
	global_store_dwordx4 v[164:165], v[160:163], off nt
	v_mul_f32_e32 v152, 0xbfb8aa3b, v78
	v_mul_f32_e32 v153, 0xbfb8aa3b, v79
	v_mul_f32_e32 v154, 0xbfb8aa3b, v80
	v_mul_f32_e32 v155, 0xbfb8aa3b, v81
	v_mul_f32_e32 v156, 0xbfb8aa3b, v70
	v_mul_f32_e32 v157, 0xbfb8aa3b, v71
	v_mul_f32_e32 v158, 0xbfb8aa3b, v72
	v_mul_f32_e32 v159, 0xbfb8aa3b, v73
	v_exp_f32_e32 v152, v152
	v_exp_f32_e32 v153, v153
	v_exp_f32_e32 v154, v154
	v_exp_f32_e32 v155, v155
	v_exp_f32_e32 v156, v156
	v_exp_f32_e32 v157, v157
	v_exp_f32_e32 v158, v158
	v_exp_f32_e32 v159, v159
	v_add_u32_e32 v166, 48, v146
	v_mad_i64_i32 v[164:165], s[22:23], v166, s11, v[150:151]
	v_add_f32_e32 v152, 1.0, v152
	v_add_f32_e32 v153, 1.0, v153
	v_add_f32_e32 v154, 1.0, v154
	v_add_f32_e32 v155, 1.0, v155
	v_add_f32_e32 v156, 1.0, v156
	v_add_f32_e32 v157, 1.0, v157
	v_add_f32_e32 v158, 1.0, v158
	v_add_f32_e32 v159, 1.0, v159
	v_rcp_f32_e32 v152, v152
	v_rcp_f32_e32 v153, v153
	v_rcp_f32_e32 v154, v154
	v_rcp_f32_e32 v155, v155
	v_rcp_f32_e32 v156, v156
	v_rcp_f32_e32 v157, v157
	v_rcp_f32_e32 v158, v158
	v_rcp_f32_e32 v159, v159
	s_nop 0
	v_mul_f32_e32 v78, v78, v152
	v_mul_f32_e32 v79, v79, v153
	v_mul_f32_e32 v80, v80, v154
	v_mul_f32_e32 v81, v81, v155
	v_mul_f32_e32 v70, v70, v156
	v_mul_f32_e32 v71, v71, v157
	v_mul_f32_e32 v72, v72, v158
	v_mul_f32_e32 v73, v73, v159
	v_mul_f32_e32 v78, v78, v74
	v_mul_f32_e32 v79, v79, v75
	v_mul_f32_e32 v80, v80, v76
	v_mul_f32_e32 v81, v81, v77
	v_mul_f32_e32 v70, v70, v66
	v_mul_f32_e32 v71, v71, v67
	v_mul_f32_e32 v72, v72, v68
	v_mul_f32_e32 v73, v73, v69
	v_cvt_pk_bf16_f32 v160, v78, v79
	v_cvt_pk_bf16_f32 v161, v80, v81
	v_cvt_pk_bf16_f32 v162, v70, v71
	v_cvt_pk_bf16_f32 v163, v72, v73
	global_store_dwordx4 v[164:165], v[160:163], off nt
	v_mul_f32_e32 v152, 0xbfb8aa3b, v62
	v_mul_f32_e32 v153, 0xbfb8aa3b, v63
	v_mul_f32_e32 v154, 0xbfb8aa3b, v64
	v_mul_f32_e32 v155, 0xbfb8aa3b, v65
	v_mul_f32_e32 v156, 0xbfb8aa3b, v54
	v_mul_f32_e32 v157, 0xbfb8aa3b, v55
	v_mul_f32_e32 v158, 0xbfb8aa3b, v56
	v_mul_f32_e32 v159, 0xbfb8aa3b, v57
	v_exp_f32_e32 v152, v152
	v_exp_f32_e32 v153, v153
	v_exp_f32_e32 v154, v154
	v_exp_f32_e32 v155, v155
	v_exp_f32_e32 v156, v156
	v_exp_f32_e32 v157, v157
	v_exp_f32_e32 v158, v158
	v_exp_f32_e32 v159, v159
	v_add_u32_e32 v166, 128, v146
	v_mad_i64_i32 v[164:165], s[22:23], v166, s11, v[150:151]
	v_add_f32_e32 v152, 1.0, v152
	v_add_f32_e32 v153, 1.0, v153
	v_add_f32_e32 v154, 1.0, v154
	v_add_f32_e32 v155, 1.0, v155
	v_add_f32_e32 v156, 1.0, v156
	v_add_f32_e32 v157, 1.0, v157
	v_add_f32_e32 v158, 1.0, v158
	v_add_f32_e32 v159, 1.0, v159
	v_rcp_f32_e32 v152, v152
	v_rcp_f32_e32 v153, v153
	v_rcp_f32_e32 v154, v154
	v_rcp_f32_e32 v155, v155
	v_rcp_f32_e32 v156, v156
	v_rcp_f32_e32 v157, v157
	v_rcp_f32_e32 v158, v158
	v_rcp_f32_e32 v159, v159
	s_nop 0
	v_mul_f32_e32 v62, v62, v152
	v_mul_f32_e32 v63, v63, v153
	v_mul_f32_e32 v64, v64, v154
	v_mul_f32_e32 v65, v65, v155
	v_mul_f32_e32 v54, v54, v156
	v_mul_f32_e32 v55, v55, v157
	v_mul_f32_e32 v56, v56, v158
	v_mul_f32_e32 v57, v57, v159
	v_mul_f32_e32 v62, v62, v58
	v_mul_f32_e32 v63, v63, v59
	v_mul_f32_e32 v64, v64, v60
	v_mul_f32_e32 v65, v65, v61
	v_mul_f32_e32 v54, v54, v50
	v_mul_f32_e32 v55, v55, v51
	v_mul_f32_e32 v56, v56, v52
	v_mul_f32_e32 v57, v57, v53
	v_cvt_pk_bf16_f32 v160, v62, v63
	v_cvt_pk_bf16_f32 v161, v64, v65
	v_cvt_pk_bf16_f32 v162, v54, v55
	v_cvt_pk_bf16_f32 v163, v56, v57
	global_store_dwordx4 v[164:165], v[160:163], off nt
	v_mul_f32_e32 v152, 0xbfb8aa3b, v46
	v_mul_f32_e32 v153, 0xbfb8aa3b, v47
	v_mul_f32_e32 v154, 0xbfb8aa3b, v48
	v_mul_f32_e32 v155, 0xbfb8aa3b, v49
	v_mul_f32_e32 v156, 0xbfb8aa3b, v38
	v_mul_f32_e32 v157, 0xbfb8aa3b, v39
	v_mul_f32_e32 v158, 0xbfb8aa3b, v40
	v_mul_f32_e32 v159, 0xbfb8aa3b, v41
	v_exp_f32_e32 v152, v152
	v_exp_f32_e32 v153, v153
	v_exp_f32_e32 v154, v154
	v_exp_f32_e32 v155, v155
	v_exp_f32_e32 v156, v156
	v_exp_f32_e32 v157, v157
	v_exp_f32_e32 v158, v158
	v_exp_f32_e32 v159, v159
	v_add_u32_e32 v166, 144, v146
	v_mad_i64_i32 v[164:165], s[22:23], v166, s11, v[150:151]
	v_add_f32_e32 v152, 1.0, v152
	v_add_f32_e32 v153, 1.0, v153
	v_add_f32_e32 v154, 1.0, v154
	v_add_f32_e32 v155, 1.0, v155
	v_add_f32_e32 v156, 1.0, v156
	v_add_f32_e32 v157, 1.0, v157
	v_add_f32_e32 v158, 1.0, v158
	v_add_f32_e32 v159, 1.0, v159
	v_rcp_f32_e32 v152, v152
	v_rcp_f32_e32 v153, v153
	v_rcp_f32_e32 v154, v154
	v_rcp_f32_e32 v155, v155
	v_rcp_f32_e32 v156, v156
	v_rcp_f32_e32 v157, v157
	v_rcp_f32_e32 v158, v158
	v_rcp_f32_e32 v159, v159
	s_nop 0
	v_mul_f32_e32 v46, v46, v152
	v_mul_f32_e32 v47, v47, v153
	v_mul_f32_e32 v48, v48, v154
	v_mul_f32_e32 v49, v49, v155
	v_mul_f32_e32 v38, v38, v156
	v_mul_f32_e32 v39, v39, v157
	v_mul_f32_e32 v40, v40, v158
	v_mul_f32_e32 v41, v41, v159
	v_mul_f32_e32 v46, v46, v42
	v_mul_f32_e32 v47, v47, v43
	v_mul_f32_e32 v48, v48, v44
	v_mul_f32_e32 v49, v49, v45
	v_mul_f32_e32 v38, v38, v34
	v_mul_f32_e32 v39, v39, v35
	v_mul_f32_e32 v40, v40, v36
	v_mul_f32_e32 v41, v41, v37
	v_cvt_pk_bf16_f32 v160, v46, v47
	v_cvt_pk_bf16_f32 v161, v48, v49
	v_cvt_pk_bf16_f32 v162, v38, v39
	v_cvt_pk_bf16_f32 v163, v40, v41
	global_store_dwordx4 v[164:165], v[160:163], off nt
	v_mul_f32_e32 v152, 0xbfb8aa3b, v30
	v_mul_f32_e32 v153, 0xbfb8aa3b, v31
	v_mul_f32_e32 v154, 0xbfb8aa3b, v32
	v_mul_f32_e32 v155, 0xbfb8aa3b, v33
	v_mul_f32_e32 v156, 0xbfb8aa3b, v22
	v_mul_f32_e32 v157, 0xbfb8aa3b, v23
	v_mul_f32_e32 v158, 0xbfb8aa3b, v24
	v_mul_f32_e32 v159, 0xbfb8aa3b, v25
	v_exp_f32_e32 v152, v152
	v_exp_f32_e32 v153, v153
	v_exp_f32_e32 v154, v154
	v_exp_f32_e32 v155, v155
	v_exp_f32_e32 v156, v156
	v_exp_f32_e32 v157, v157
	v_exp_f32_e32 v158, v158
	v_exp_f32_e32 v159, v159
	v_add_u32_e32 v166, 160, v146
	v_mad_i64_i32 v[164:165], s[22:23], v166, s11, v[150:151]
	v_add_f32_e32 v152, 1.0, v152
	v_add_f32_e32 v153, 1.0, v153
	v_add_f32_e32 v154, 1.0, v154
	v_add_f32_e32 v155, 1.0, v155
	v_add_f32_e32 v156, 1.0, v156
	v_add_f32_e32 v157, 1.0, v157
	v_add_f32_e32 v158, 1.0, v158
	v_add_f32_e32 v159, 1.0, v159
	v_rcp_f32_e32 v152, v152
	v_rcp_f32_e32 v153, v153
	v_rcp_f32_e32 v154, v154
	v_rcp_f32_e32 v155, v155
	v_rcp_f32_e32 v156, v156
	v_rcp_f32_e32 v157, v157
	v_rcp_f32_e32 v158, v158
	v_rcp_f32_e32 v159, v159
	s_nop 0
	v_mul_f32_e32 v30, v30, v152
	v_mul_f32_e32 v31, v31, v153
	v_mul_f32_e32 v32, v32, v154
	v_mul_f32_e32 v33, v33, v155
	v_mul_f32_e32 v22, v22, v156
	v_mul_f32_e32 v23, v23, v157
	v_mul_f32_e32 v24, v24, v158
	v_mul_f32_e32 v25, v25, v159
	v_mul_f32_e32 v30, v30, v26
	v_mul_f32_e32 v31, v31, v27
	v_mul_f32_e32 v32, v32, v28
	v_mul_f32_e32 v33, v33, v29
	v_mul_f32_e32 v22, v22, v18
	v_mul_f32_e32 v23, v23, v19
	v_mul_f32_e32 v24, v24, v20
	v_mul_f32_e32 v25, v25, v21
	v_cvt_pk_bf16_f32 v160, v30, v31
	v_cvt_pk_bf16_f32 v161, v32, v33
	v_cvt_pk_bf16_f32 v162, v22, v23
	v_cvt_pk_bf16_f32 v163, v24, v25
	global_store_dwordx4 v[164:165], v[160:163], off nt
	v_mul_f32_e32 v152, 0xbfb8aa3b, v14
	v_mul_f32_e32 v153, 0xbfb8aa3b, v15
	v_mul_f32_e32 v154, 0xbfb8aa3b, v16
	v_mul_f32_e32 v155, 0xbfb8aa3b, v17
	v_mul_f32_e32 v156, 0xbfb8aa3b, v6
	v_mul_f32_e32 v157, 0xbfb8aa3b, v7
	v_mul_f32_e32 v158, 0xbfb8aa3b, v8
	v_mul_f32_e32 v159, 0xbfb8aa3b, v9
	v_exp_f32_e32 v152, v152
	v_exp_f32_e32 v153, v153
	v_exp_f32_e32 v154, v154
	v_exp_f32_e32 v155, v155
	v_exp_f32_e32 v156, v156
	v_exp_f32_e32 v157, v157
	v_exp_f32_e32 v158, v158
	v_exp_f32_e32 v159, v159
	v_add_u32_e32 v166, 176, v146
	v_mad_i64_i32 v[164:165], s[22:23], v166, s11, v[150:151]
	v_add_f32_e32 v152, 1.0, v152
	v_add_f32_e32 v153, 1.0, v153
	v_add_f32_e32 v154, 1.0, v154
	v_add_f32_e32 v155, 1.0, v155
	v_add_f32_e32 v156, 1.0, v156
	v_add_f32_e32 v157, 1.0, v157
	v_add_f32_e32 v158, 1.0, v158
	v_add_f32_e32 v159, 1.0, v159
	v_rcp_f32_e32 v152, v152
	v_rcp_f32_e32 v153, v153
	v_rcp_f32_e32 v154, v154
	v_rcp_f32_e32 v155, v155
	v_rcp_f32_e32 v156, v156
	v_rcp_f32_e32 v157, v157
	v_rcp_f32_e32 v158, v158
	v_rcp_f32_e32 v159, v159
	s_mov_b64 s[22:23], s[14:15]
	v_mul_f32_e32 v14, v14, v152
	v_mul_f32_e32 v15, v15, v153
	v_mul_f32_e32 v16, v16, v154
	v_mul_f32_e32 v17, v17, v155
	v_mul_f32_e32 v6, v6, v156
	v_mul_f32_e32 v7, v7, v157
	v_mul_f32_e32 v8, v8, v158
	v_mul_f32_e32 v9, v9, v159
	v_mul_f32_e32 v14, v14, v10
	v_mul_f32_e32 v15, v15, v11
	v_mul_f32_e32 v16, v16, v12
	v_mul_f32_e32 v17, v17, v13
	v_mul_f32_e32 v6, v6, v2
	v_mul_f32_e32 v7, v7, v3
	v_mul_f32_e32 v8, v8, v4
	v_mul_f32_e32 v9, v9, v5
	v_cvt_pk_bf16_f32 v160, v14, v15
	v_cvt_pk_bf16_f32 v161, v16, v17
	v_cvt_pk_bf16_f32 v162, v6, v7
	v_cvt_pk_bf16_f32 v163, v8, v9
	global_store_dwordx4 v[164:165], v[160:163], off nt
	s_cbranch_vccz .LBB0_1202
	s_waitcnt vmcnt(0)
	s_cmpk_gt_u32 s24, 0xff
	s_cbranch_scc1 .LBB0_1210
	s_barrier
